# weight-conversion tile walk runs k-tile fastest (concurrent workgroups write adjacent 128-byte segments of the same bf16 rows)
# baseline (speedup 1.0000x reference)
; __device__ __forceinline__ void phase0(PP p, unsigned char* shm) {
;     ...
;     constexpr int C_IN = 32 * 14, C_OUT = 32 * 8, C_XQ = 32 * 2, C_XO = 8 * 8, C_UP = 32 * 32, C_DN = 128 * 8, C_GLU = 8 * 2, C_POOL = 16, C_PW = 8 * 2;
;     constexpr int C_LAYER = C_IN + C_OUT + 3 * C_XQ + C_XO + C_UP + C_DN + C_GLU + C_POOL + C_PW;
;     for (int it = bid_fresh(); it < DEPTH * C_LAYER; it += gridDim.x) {
;         const int l = it / C_LAYER; int r = it % C_LAYER;
;         if (r < C_IN) { tconv_tile_w(p->in[5] + (size_t)l * D * INW, INW, r / 14, r % 14, (bf16_t*)(ws + WS_WIN) + (size_t)l * INW * D, D, tile, p->in[4] + (size_t)l * D); continue; } r -= C_IN;
;         if (r < C_OUT) { tconv_tile_w(p->in[23] + (size_t)l * D * D, D, r / 8, r % 8, (bf16_t*)(ws + WS_WOUT) + (size_t)l * D * D, D, tile, p->in[22] + (size_t)l * D); continue; } r -= C_OUT;
;         if (r < C_XQ) { tconv_tile_w(p->in[25] + (size_t)l * D * 512, 512, r / 2, r % 2, (bf16_t*)(ws + WS_WXQ) + (size_t)l * 512 * D, D, tile, p->in[24] + (size_t)l * D); continue; } r -= C_XQ;
;         if (r < C_XQ) { tconv_tile_w(p->in[26] + (size_t)l * D * 512, 512, r / 2, r % 2, (bf16_t*)(ws + WS_WKV) + (size_t)(l * 1024) * D, D, tile); continue; } r -= C_XQ;
;         if (r < C_XQ) { tconv_tile_w(p->in[27] + (size_t)l * D * 512, 512, r / 2, r % 2, (bf16_t*)(ws + WS_WKV) + (size_t)(l * 1024 + 512) * D, D, tile); continue; } r -= C_XQ;
;         if (r < C_XO) { tconv_tile_w(p->in[28] + (size_t)l * 512 * D, D, r / 8, r % 8, (bf16_t*)(ws + WS_WXO) + (size_t)l * D * 512, 512, tile); continue; } r -= C_XO;
;         if (r < C_UP) { tconv_tile_w(p->in[30] + (size_t)l * D * DFF, DFF, r / 32, r % 32, (bf16_t*)(ws + WS_WUP) + (size_t)l * DFF * D, D, tile, p->in[29] + (size_t)l * D); continue; } r -= C_UP;
;         if (r < C_DN) { if (l == 0) tconv_tile_w(p->in[31] + (size_t)l * DFF * D, D, r / 8, r % 8, (bf16_t*)(ws + WS_WDN) + (size_t)l * D * DFF, DFF, tile); continue; } r -= C_DN;
;         bf16_t* wsm = (bf16_t*)(ws + WS_WSM) + (size_t)l * 1536 * 512;
;         if (r < C_GLU) { tconv_tile_w(p->in[14] + (size_t)l * 512 * 512, 512, r / 2, r % 2, wsm, 512, tile); continue; } r -= C_GLU;
;         if (r < C_POOL) { const int gi = r >> 2, q = r & 3; tconv_tile(p->in[15] + (size_t)(l * 4 + gi) * 128 * 128, 128, q >> 1, q & 1, wsm + (size_t)(512 + gi * 128) * 512 + gi * 128, 512, tile); continue; } r -= C_POOL;
.Ltc_found_3:
	s_cmp_eq_u32 s62, 0
	s_cbranch_scc1 .Ltc_noseg_7
	s_cmp_eq_u32 s28, 0
	s_cbranch_scc0 .Ltc_k_25
	s_mov_b32 s30, 448
	s_mov_b32 s55, 0x28
	s_mov_b32 s34, 0x3800
	s_mov_b32 s31, 0x800
	s_mov_b32 s33, 32
	s_mov_b32 s35, 0x1000
	s_mov_b32 s56, 0x0
	s_mov_b32 s57, 0xe00000
	s_mov_b32 s58, 0x1c00000
	s_mov_b32 s42, 0x20
	s_branch .Ltc_segdone_24
.Ltc_k_25:
	s_cmp_eq_u32 s28, 1
	s_cbranch_scc0 .Ltc_k_26
	s_mov_b32 s30, 256
	s_mov_b32 s55, 0xb8
	s_mov_b32 s34, 0x2000
	s_mov_b32 s31, 0x800
	s_mov_b32 s33, 32
	s_mov_b32 s35, 0x1000
	s_mov_b32 s56, 0x3800000
	s_mov_b32 s57, 0x800000
	s_mov_b32 s58, 0x1000000
	s_mov_b32 s42, 0xb0
	s_branch .Ltc_segdone_24
.Ltc_k_26:
	s_cmp_eq_u32 s28, 2
	s_cbranch_scc0 .Ltc_k_27
	s_mov_b32 s30, 64
	s_mov_b32 s55, 0xc8
	s_mov_b32 s34, 0x800
	s_mov_b32 s31, 0x800
	s_mov_b32 s33, 32
	s_mov_b32 s35, 0x1000
	s_mov_b32 s56, 0x5800000
	s_mov_b32 s57, 0x200000
	s_mov_b32 s58, 0x400000
	s_mov_b32 s42, 0xc0
	s_branch .Ltc_segdone_24
.Ltc_k_27:
	s_cmp_eq_u32 s28, 3
	s_cbranch_scc0 .Ltc_k_28
	s_mov_b32 s30, 64
	s_mov_b32 s55, 0xd0
	s_mov_b32 s34, 0x800
	s_mov_b32 s31, 0x800
	s_mov_b32 s33, 32
	s_mov_b32 s35, 0x1000
	s_mov_b32 s56, 0x6000000
	s_mov_b32 s57, 0x400000
	s_mov_b32 s58, 0x400000
	s_mov_b32 s42, 0x0
	s_branch .Ltc_segdone_24
.Ltc_k_28:
	s_cmp_eq_u32 s28, 4
	s_cbranch_scc0 .Ltc_k_29
	s_mov_b32 s30, 64
	s_mov_b32 s55, 0xd8
	s_mov_b32 s34, 0x800
	s_mov_b32 s31, 0x800
	s_mov_b32 s33, 32
	s_mov_b32 s35, 0x1000
	s_mov_b32 s56, 0x6200000
	s_mov_b32 s57, 0x400000
	s_mov_b32 s58, 0x400000
	s_mov_b32 s42, 0x0
	s_branch .Ltc_segdone_24

; __device__ __forceinline__ void phase0(PP p, unsigned char* shm) {
;     ...
;         if (r < C_DN) { if (l == 0) tconv_tile_w(p->in[31] + (size_t)l * DFF * D, D, r / 8, r % 8, (bf16_t*)(ws + WS_WDN) + (size_t)l * D * DFF, DFF, tile); continue; } r -= C_DN;
;         bf16_t* wsm = (bf16_t*)(ws + WS_WSM) + (size_t)l * 1536 * 512;
;         if (r < C_GLU) { tconv_tile_w(p->in[14] + (size_t)l * 512 * 512, 512, r / 2, r % 2, wsm, 512, tile); continue; } r -= C_GLU;
;         if (r < C_POOL) { const int gi = r >> 2, q = r & 3; tconv_tile(p->in[15] + (size_t)(l * 4 + gi) * 128 * 128, 128, q >> 1, q & 1, wsm + (size_t)(512 + gi * 128) * 512 + gi * 128, 512, tile); continue; } r -= C_POOL;
;         tconv_tile_w(p->in[21] + (size_t)l * 512 * 512, 512, r / 2, r % 2, wsm + (size_t)1024 * 512, 512, tile);
.Ltc_k_31:
	s_cmp_eq_u32 s28, 7
	s_cbranch_scc0 .Ltc_k_32
	s_mov_b32 s30, 16
	s_mov_b32 s55, 0x70
	s_mov_b32 s34, 0x800
	s_mov_b32 s31, 0x2000
	s_mov_b32 s33, 8
	s_mov_b32 s35, 0x400
	s_mov_b32 s56, 0x17800000
	s_mov_b32 s57, 0x180000
	s_mov_b32 s58, 0x100000
	s_mov_b32 s42, 0x0
	s_branch .Ltc_segdone_24
.Ltc_k_32:
	s_cmp_eq_u32 s28, 8
	s_cbranch_scc0 .Ltc_k_33
	s_mov_b32 s30, 16
	s_mov_b32 s55, 0xa8
	s_mov_b32 s34, 0x800
	s_mov_b32 s31, 0x2000
	s_mov_b32 s33, 8
	s_mov_b32 s35, 0x400
	s_mov_b32 s56, 0x17900000
	s_mov_b32 s57, 0x180000
	s_mov_b32 s58, 0x100000
	s_mov_b32 s42, 0x0
	s_branch .Ltc_segdone_24
.Ltc_k_33:
	s_mov_b32 s30, 1024
	s_mov_b32 s55, 0xf8
	s_mov_b32 s34, 0x2000
	s_mov_b32 s31, 0x200
	s_mov_b32 s33, 128
	s_mov_b32 s35, 0x4000
	s_mov_b32 s56, 0xf800000
	s_mov_b32 s57, 0x2000000
	s_mov_b32 s58, 0x4000000
	s_mov_b32 s42, 0x0

; __device__ __forceinline__ void tconv_tile_w(const float* src, int N, int kb, int nb, bf16_t* dst, int ldd, float* tile, const float* kscale = nullptr) {
;     ...
;         v[p] = __builtin_nontemporal_load((const f32x4*)(src + (size_t)(kb * 64 + r) * N + nb * 256 + c4 * 4)); }
;     if (kscale) {
; __device__ __forceinline__ void phase0(PP p, unsigned char* shm) {
;     ...
;         if (r < C_IN) { tconv_tile_w(p->in[5] + (size_t)l * D * INW, INW, r / 14, r % 14, (bf16_t*)(ws + WS_WIN) + (size_t)l * INW * D, D, tile, p->in[4] + (size_t)l * D); continue; } r -= C_IN;
;         if (r < C_OUT) { tconv_tile_w(p->in[23] + (size_t)l * D * D, D, r / 8, r % 8, (bf16_t*)(ws + WS_WOUT) + (size_t)l * D * D, D, tile, p->in[22] + (size_t)l * D); continue; } r -= C_OUT;
;         if (r < C_XQ) { tconv_tile_w(p->in[25] + (size_t)l * D * 512, 512, r / 2, r % 2, (bf16_t*)(ws + WS_WXQ) + (size_t)l * 512 * D, D, tile, p->in[24] + (size_t)l * D); continue; } r -= C_XQ;
;         if (r < C_XQ) { tconv_tile_w(p->in[26] + (size_t)l * D * 512, 512, r / 2, r % 2, (bf16_t*)(ws + WS_WKV) + (size_t)(l * 1024) * D, D, tile); continue; } r -= C_XQ;
;         if (r < C_XQ) { tconv_tile_w(p->in[27] + (size_t)l * D * 512, 512, r / 2, r % 2, (bf16_t*)(ws + WS_WKV) + (size_t)(l * 1024 + 512) * D, D, tile); continue; } r -= C_XQ;
;         if (r < C_XO) { tconv_tile_w(p->in[28] + (size_t)l * 512 * D, D, r / 8, r % 8, (bf16_t*)(ws + WS_WXO) + (size_t)l * D * 512, 512, tile); continue; } r -= C_XO;
;         if (r < C_UP) { tconv_tile_w(p->in[30] + (size_t)l * D * DFF, DFF, r / 32, r % 32, (bf16_t*)(ws + WS_WUP) + (size_t)l * DFF * D, D, tile, p->in[29] + (size_t)l * D); continue; } r -= C_UP;
;         if (r < C_DN) { if (l == 0) tconv_tile_w(p->in[31] + (size_t)l * DFF * D, D, r / 8, r % 8, (bf16_t*)(ws + WS_WDN) + (size_t)l * D * DFF, DFF, tile); continue; } r -= C_DN;
;         bf16_t* wsm = (bf16_t*)(ws + WS_WSM) + (size_t)l * 1536 * 512;
;         if (r < C_GLU) { tconv_tile_w(p->in[14] + (size_t)l * 512 * 512, 512, r / 2, r % 2, wsm, 512, tile); continue; } r -= C_GLU;
;         if (r < C_POOL) { const int gi = r >> 2, q = r & 3; tconv_tile(p->in[15] + (size_t)(l * 4 + gi) * 128 * 128, 128, q >> 1, q & 1, wsm + (size_t)(512 + gi * 128) * 512 + gi * 128, 512, tile); continue; } r -= C_POOL;
;         tconv_tile_w(p->in[21] + (size_t)l * 512 * 512, 512, r / 2, r % 2, wsm + (size_t)1024 * 512, 512, tile);
.Ltc_noseg_7:
	s_mul_i32 s2, s29, s31
	s_lshr_b32 s2, s2, 16
	s_mul_i32 s3, s2, s33
	s_sub_u32 s3, s29, s3
	s_mov_b32 s4, s2
	s_mov_b32 s2, s3
	s_mov_b32 s3, s4
	s_lshl_b32 s4, s2, 6
	s_add_u32 s4, s4, s54
	s_mul_i32 s5, s4, s34
	s_lshl_b32 s6, s3, 10
	s_add_u32 s5, s5, s6
	s_add_u32 s44, s36, s5
	s_addc_u32 s45, s37, 0
	s_lshl_b32 s6, s3, 8
	s_mul_i32 s6, s6, s35
	s_lshl_b32 s7, s2, 7
	s_add_u32 s6, s6, s7
	s_add_u32 s46, s38, s6
	s_addc_u32 s47, s39, 0
	s_mov_b32 s48, s35
	s_mov_b32 s49, s34
	s_mov_b32 s61, s42
	s_cmp_eq_u32 s42, 0
	s_cbranch_scc1 .Ltc_tnosc_36
	s_lshl_b32 s4, s4, 2
	s_load_dwordx8 s[76:83], s[40:41], s4
